# retention fix-up pass rewritten by hand: 8 consecutive lanes cover one row's contiguous 128 B (coalesced b128 loads/stores) instead of one 25.6KB-strided row per lane; same arithmetic
# speedup vs baseline: 1.0090x; 1.0090x over previous
; __device__ __forceinline__ unsigned cvt_pk_bf16(float lo, float hi) { unsigned r; asm volatile("v_cvt_pk_bf16_f32 %0, %1, %2" : "=v"(r) : "v"(lo), "v"(hi)); return r; }
; __device__ __forceinline__ float bflo(unsigned w) { return __uint_as_float(w << 16); }
; __device__ __forceinline__ float bfhi(unsigned w) { return __uint_as_float(w & 0xffff0000u); }
; __device__ __forceinline__ void ret_unit(LAS unsigned char* lds, bf16_t* proj, float* out, float* rss, unsigned* cnt, int unit, bool same_xcd) {
;     ...
; #pragma unroll 1
;     for (int it = 0; it < 4; ++it) { const size_t row = rowbase + tid + 512 * it;
;         const float sq = __hip_atomic_load(rss + row * 4 + h, __ATOMIC_RELAXED, __HIP_MEMORY_SCOPE_AGENT);
;         const float rs = rsqrtf(sq * (1.0f / 512.0f) + EPS);
;         u32x4* up = (u32x4*)(proj + row * DIN + VR_OFF + 512 * h + 64 * es);
;         u32x4 v[8];
; #pragma unroll
;         for (int pc = 0; pc < 8; ++pc) v[pc] = up[pc];
; #pragma unroll
;         for (int pc = 0; pc < 8; ++pc) { u32x4 o;
;             o.x = cvt_pk_bf16(bflo(v[pc].x) * rs, bfhi(v[pc].x) * rs); o.y = cvt_pk_bf16(bflo(v[pc].y) * rs, bfhi(v[pc].y) * rs);
;             o.z = cvt_pk_bf16(bflo(v[pc].z) * rs, bfhi(v[pc].z) * rs); o.w = cvt_pk_bf16(bflo(v[pc].w) * rs, bfhi(v[pc].w) * rs);
;             up[pc] = o; } }
.LBB0_1299:
	s_or_b64 exec, exec, s[0:1]
	v_readlane_b32 s0, v249, 33
	s_add_u32 s0, s94, s0
	s_addc_u32 s1, s95, 0
	v_lshl_add_u64 v[0:1], v[174:175], 0, s[0:1]
	s_lshl_b32 s0, s33, 10
	s_add_u32 s0, s63, s0
	s_addc_u32 s1, s70, 0
	v_lshl_add_u64 v[2:3], v[176:177], 0, s[0:1]
	s_mov_b64 s[0:1], 0
	s_barrier
	v_lshrrev_b32_e32 v36, 3, v208
	v_sub_u32_e32 v37, v208, v36
	v_and_b32_e32 v38, 7, v208
	v_lshlrev_b32_e32 v39, 4, v37
	v_mul_u32_u24_e32 v40, 0x6400, v37
	v_lshlrev_b32_e32 v41, 4, v38
	v_add_u32_e32 v40, 64, v40
	v_sub_u32_e32 v40, v40, v41
	v_sub_co_u32_e32 v0, vcc, v0, v39
	s_nop 1
	v_subbrev_co_u32_e32 v1, vcc, 0, v1, vcc
	v_sub_co_u32_e32 v2, vcc, v2, v40
	s_nop 1
	v_subbrev_co_u32_e32 v3, vcc, 0, v3, vcc
	v_mov_b32_e32 v60, 0x358637bd
	v_mov_b32_e32 v62, 0x190000
	v_mov_b32_e32 v63, 0
	v_mov_b32_e32 v64, 0x1000
	v_mov_b32_e32 v65, 0
	s_mov_b32 s6, 0x800000
	s_mov_b64 s[2:3], 0xc80000
.Lretfix_loop:
	v_lshl_add_u64 v[4:5], v[0:1], 0, s[0:1]
	v_lshl_add_u64 v[6:7], v[4:5], 0, v[64:65]
	global_load_dword v36, v[4:5], off sc1
	global_load_dword v37, v[4:5], off offset:1024 sc1
	global_load_dword v38, v[4:5], off offset:2048 sc1
	global_load_dword v39, v[4:5], off offset:3072 sc1
	global_load_dword v40, v[6:7], off sc1
	global_load_dword v41, v[6:7], off offset:1024 sc1
	global_load_dword v42, v[6:7], off offset:2048 sc1
	global_load_dword v43, v[6:7], off offset:3072 sc1
	v_mov_b32_e32 v44, v2
	v_mov_b32_e32 v45, v3
	v_lshl_add_u64 v[46:47], v[44:45], 0, v[62:63]
	v_lshl_add_u64 v[48:49], v[46:47], 0, v[62:63]
	v_lshl_add_u64 v[50:51], v[48:49], 0, v[62:63]
	v_lshl_add_u64 v[52:53], v[50:51], 0, v[62:63]
	v_lshl_add_u64 v[54:55], v[52:53], 0, v[62:63]
	v_lshl_add_u64 v[56:57], v[54:55], 0, v[62:63]
	v_lshl_add_u64 v[58:59], v[56:57], 0, v[62:63]
	s_nop 0
	global_load_dwordx4 v[4:7], v[44:45], off
	global_load_dwordx4 v[8:11], v[46:47], off
	global_load_dwordx4 v[12:15], v[48:49], off
	global_load_dwordx4 v[16:19], v[50:51], off
	global_load_dwordx4 v[20:23], v[52:53], off
	global_load_dwordx4 v[24:27], v[54:55], off
	global_load_dwordx4 v[28:31], v[56:57], off
	global_load_dwordx4 v[32:35], v[58:59], off
	s_waitcnt vmcnt(8)
	v_fmamk_f32 v36, v36, 0x3b000000, v60
	v_fmamk_f32 v37, v37, 0x3b000000, v60
	v_fmamk_f32 v38, v38, 0x3b000000, v60
	v_fmamk_f32 v39, v39, 0x3b000000, v60
	v_fmamk_f32 v40, v40, 0x3b000000, v60
	v_fmamk_f32 v41, v41, 0x3b000000, v60
	v_fmamk_f32 v42, v42, 0x3b000000, v60
	v_fmamk_f32 v43, v43, 0x3b000000, v60
	v_mul_f32_e32 v61, 0x4b800000, v36
	v_cmp_gt_f32_e32 vcc, s6, v36
	s_nop 1
	v_cndmask_b32_e32 v36, v36, v61, vcc
	v_rsq_f32_e32 v36, v36
	s_nop 0
	v_mul_f32_e32 v61, 0x45800000, v36
	v_cndmask_b32_e32 v36, v36, v61, vcc
	v_mul_f32_e32 v61, 0x4b800000, v37
	v_cmp_gt_f32_e32 vcc, s6, v37
	s_nop 1
	v_cndmask_b32_e32 v37, v37, v61, vcc
	v_rsq_f32_e32 v37, v37
	s_nop 0
	v_mul_f32_e32 v61, 0x45800000, v37
	v_cndmask_b32_e32 v37, v37, v61, vcc
	v_mul_f32_e32 v61, 0x4b800000, v38
	v_cmp_gt_f32_e32 vcc, s6, v38
	s_nop 1
	v_cndmask_b32_e32 v38, v38, v61, vcc
	v_rsq_f32_e32 v38, v38
	s_nop 0
	v_mul_f32_e32 v61, 0x45800000, v38
	v_cndmask_b32_e32 v38, v38, v61, vcc
	v_mul_f32_e32 v61, 0x4b800000, v39
	v_cmp_gt_f32_e32 vcc, s6, v39
	s_nop 1
	v_cndmask_b32_e32 v39, v39, v61, vcc
	v_rsq_f32_e32 v39, v39
	s_nop 0
	v_mul_f32_e32 v61, 0x45800000, v39
	v_cndmask_b32_e32 v39, v39, v61, vcc
	v_mul_f32_e32 v61, 0x4b800000, v40
	v_cmp_gt_f32_e32 vcc, s6, v40
	s_nop 1
	v_cndmask_b32_e32 v40, v40, v61, vcc
	v_rsq_f32_e32 v40, v40
	s_nop 0
	v_mul_f32_e32 v61, 0x45800000, v40
	v_cndmask_b32_e32 v40, v40, v61, vcc
	v_mul_f32_e32 v61, 0x4b800000, v41
	v_cmp_gt_f32_e32 vcc, s6, v41
	s_nop 1
	v_cndmask_b32_e32 v41, v41, v61, vcc
	v_rsq_f32_e32 v41, v41
	s_nop 0
	v_mul_f32_e32 v61, 0x45800000, v41
	v_cndmask_b32_e32 v41, v41, v61, vcc
	v_mul_f32_e32 v61, 0x4b800000, v42
	v_cmp_gt_f32_e32 vcc, s6, v42
	s_nop 1
	v_cndmask_b32_e32 v42, v42, v61, vcc
	v_rsq_f32_e32 v42, v42
	s_nop 0
	v_mul_f32_e32 v61, 0x45800000, v42
	v_cndmask_b32_e32 v42, v42, v61, vcc
	v_mul_f32_e32 v61, 0x4b800000, v43
	v_cmp_gt_f32_e32 vcc, s6, v43
	s_nop 1
	v_cndmask_b32_e32 v43, v43, v61, vcc
	v_rsq_f32_e32 v43, v43
	s_nop 0
	v_mul_f32_e32 v61, 0x45800000, v43
	v_cndmask_b32_e32 v43, v43, v61, vcc
	s_waitcnt vmcnt(7)
	v_lshlrev_b32_e32 v66, 16, v4
	v_and_b32_e32 v67, 0xffff0000, v4
	v_mul_f32_e32 v66, v36, v66
	v_mul_f32_e32 v67, v36, v67
	v_cvt_pk_bf16_f32 v4, v66, v67
	v_lshlrev_b32_e32 v68, 16, v5
	v_and_b32_e32 v69, 0xffff0000, v5
	v_mul_f32_e32 v68, v36, v68
	v_mul_f32_e32 v69, v36, v69
	v_cvt_pk_bf16_f32 v5, v68, v69
	v_lshlrev_b32_e32 v66, 16, v6
	v_and_b32_e32 v67, 0xffff0000, v6
	v_mul_f32_e32 v66, v36, v66
	v_mul_f32_e32 v67, v36, v67
	v_cvt_pk_bf16_f32 v6, v66, v67
	v_lshlrev_b32_e32 v68, 16, v7
	v_and_b32_e32 v69, 0xffff0000, v7
	v_mul_f32_e32 v68, v36, v68
	v_mul_f32_e32 v69, v36, v69
	v_cvt_pk_bf16_f32 v7, v68, v69
	s_nop 1
	global_store_dwordx4 v[44:45], v[4:7], off
	s_waitcnt vmcnt(7)
; __device__ __forceinline__ unsigned cvt_pk_bf16(float lo, float hi) { unsigned r; asm volatile("v_cvt_pk_bf16_f32 %0, %1, %2" : "=v"(r) : "v"(lo), "v"(hi)); return r; }
; __device__ __forceinline__ float bflo(unsigned w) { return __uint_as_float(w << 16); }
; __device__ __forceinline__ float bfhi(unsigned w) { return __uint_as_float(w & 0xffff0000u); }
; __device__ __forceinline__ void ret_unit(LAS unsigned char* lds, bf16_t* proj, float* out, float* rss, unsigned* cnt, int unit, bool same_xcd) {
;     ...
;         u32x4 v[8];
; #pragma unroll
;         for (int pc = 0; pc < 8; ++pc) v[pc] = up[pc];
; #pragma unroll
;         for (int pc = 0; pc < 8; ++pc) { u32x4 o;
;             o.x = cvt_pk_bf16(bflo(v[pc].x) * rs, bfhi(v[pc].x) * rs); o.y = cvt_pk_bf16(bflo(v[pc].y) * rs, bfhi(v[pc].y) * rs);
;             o.z = cvt_pk_bf16(bflo(v[pc].z) * rs, bfhi(v[pc].z) * rs); o.w = cvt_pk_bf16(bflo(v[pc].w) * rs, bfhi(v[pc].w) * rs);
;             up[pc] = o; } }
	v_lshlrev_b32_e32 v66, 16, v8
	v_and_b32_e32 v67, 0xffff0000, v8
	v_mul_f32_e32 v66, v37, v66
	v_mul_f32_e32 v67, v37, v67
	v_cvt_pk_bf16_f32 v8, v66, v67
	v_lshlrev_b32_e32 v68, 16, v9
	v_and_b32_e32 v69, 0xffff0000, v9
	v_mul_f32_e32 v68, v37, v68
	v_mul_f32_e32 v69, v37, v69
	v_cvt_pk_bf16_f32 v9, v68, v69
	v_lshlrev_b32_e32 v66, 16, v10
	v_and_b32_e32 v67, 0xffff0000, v10
	v_mul_f32_e32 v66, v37, v66
	v_mul_f32_e32 v67, v37, v67
	v_cvt_pk_bf16_f32 v10, v66, v67
	v_lshlrev_b32_e32 v68, 16, v11
	v_and_b32_e32 v69, 0xffff0000, v11
	v_mul_f32_e32 v68, v37, v68
	v_mul_f32_e32 v69, v37, v69
	v_cvt_pk_bf16_f32 v11, v68, v69
	s_nop 1
	global_store_dwordx4 v[46:47], v[8:11], off
	s_waitcnt vmcnt(7)
	v_lshlrev_b32_e32 v66, 16, v12
	v_and_b32_e32 v67, 0xffff0000, v12
	v_mul_f32_e32 v66, v38, v66
	v_mul_f32_e32 v67, v38, v67
	v_cvt_pk_bf16_f32 v12, v66, v67
	v_lshlrev_b32_e32 v68, 16, v13
	v_and_b32_e32 v69, 0xffff0000, v13
	v_mul_f32_e32 v68, v38, v68
	v_mul_f32_e32 v69, v38, v69
	v_cvt_pk_bf16_f32 v13, v68, v69
	v_lshlrev_b32_e32 v66, 16, v14
	v_and_b32_e32 v67, 0xffff0000, v14
	v_mul_f32_e32 v66, v38, v66
	v_mul_f32_e32 v67, v38, v67
	v_cvt_pk_bf16_f32 v14, v66, v67
	v_lshlrev_b32_e32 v68, 16, v15
	v_and_b32_e32 v69, 0xffff0000, v15
	v_mul_f32_e32 v68, v38, v68
	v_mul_f32_e32 v69, v38, v69
	v_cvt_pk_bf16_f32 v15, v68, v69
	s_nop 1
	global_store_dwordx4 v[48:49], v[12:15], off
	s_waitcnt vmcnt(7)
	v_lshlrev_b32_e32 v66, 16, v16
	v_and_b32_e32 v67, 0xffff0000, v16
	v_mul_f32_e32 v66, v39, v66
	v_mul_f32_e32 v67, v39, v67
	v_cvt_pk_bf16_f32 v16, v66, v67
	v_lshlrev_b32_e32 v68, 16, v17
	v_and_b32_e32 v69, 0xffff0000, v17
	v_mul_f32_e32 v68, v39, v68
	v_mul_f32_e32 v69, v39, v69
	v_cvt_pk_bf16_f32 v17, v68, v69
	v_lshlrev_b32_e32 v66, 16, v18
	v_and_b32_e32 v67, 0xffff0000, v18
	v_mul_f32_e32 v66, v39, v66
	v_mul_f32_e32 v67, v39, v67
	v_cvt_pk_bf16_f32 v18, v66, v67
	v_lshlrev_b32_e32 v68, 16, v19
	v_and_b32_e32 v69, 0xffff0000, v19
	v_mul_f32_e32 v68, v39, v68
	v_mul_f32_e32 v69, v39, v69
	v_cvt_pk_bf16_f32 v19, v68, v69
	s_nop 1
	global_store_dwordx4 v[50:51], v[16:19], off
	s_waitcnt vmcnt(7)
	v_lshlrev_b32_e32 v66, 16, v20
	v_and_b32_e32 v67, 0xffff0000, v20
	v_mul_f32_e32 v66, v40, v66
	v_mul_f32_e32 v67, v40, v67
	v_cvt_pk_bf16_f32 v20, v66, v67
	v_lshlrev_b32_e32 v68, 16, v21
	v_and_b32_e32 v69, 0xffff0000, v21
	v_mul_f32_e32 v68, v40, v68
	v_mul_f32_e32 v69, v40, v69
	v_cvt_pk_bf16_f32 v21, v68, v69
	v_lshlrev_b32_e32 v66, 16, v22
	v_and_b32_e32 v67, 0xffff0000, v22
	v_mul_f32_e32 v66, v40, v66
	v_mul_f32_e32 v67, v40, v67
	v_cvt_pk_bf16_f32 v22, v66, v67
	v_lshlrev_b32_e32 v68, 16, v23
	v_and_b32_e32 v69, 0xffff0000, v23
	v_mul_f32_e32 v68, v40, v68
	v_mul_f32_e32 v69, v40, v69
	v_cvt_pk_bf16_f32 v23, v68, v69
	s_nop 1
	global_store_dwordx4 v[52:53], v[20:23], off
	s_waitcnt vmcnt(7)
	v_lshlrev_b32_e32 v66, 16, v24
	v_and_b32_e32 v67, 0xffff0000, v24
	v_mul_f32_e32 v66, v41, v66
	v_mul_f32_e32 v67, v41, v67
	v_cvt_pk_bf16_f32 v24, v66, v67
	v_lshlrev_b32_e32 v68, 16, v25
	v_and_b32_e32 v69, 0xffff0000, v25
	v_mul_f32_e32 v68, v41, v68
	v_mul_f32_e32 v69, v41, v69
	v_cvt_pk_bf16_f32 v25, v68, v69
	v_lshlrev_b32_e32 v66, 16, v26
	v_and_b32_e32 v67, 0xffff0000, v26
	v_mul_f32_e32 v66, v41, v66
	v_mul_f32_e32 v67, v41, v67
	v_cvt_pk_bf16_f32 v26, v66, v67
	v_lshlrev_b32_e32 v68, 16, v27
	v_and_b32_e32 v69, 0xffff0000, v27
	v_mul_f32_e32 v68, v41, v68
	v_mul_f32_e32 v69, v41, v69
	v_cvt_pk_bf16_f32 v27, v68, v69
	s_nop 1
	global_store_dwordx4 v[54:55], v[24:27], off
	s_waitcnt vmcnt(7)
	v_lshlrev_b32_e32 v66, 16, v28
	v_and_b32_e32 v67, 0xffff0000, v28
	v_mul_f32_e32 v66, v42, v66
	v_mul_f32_e32 v67, v42, v67
	v_cvt_pk_bf16_f32 v28, v66, v67
	v_lshlrev_b32_e32 v68, 16, v29
	v_and_b32_e32 v69, 0xffff0000, v29
	v_mul_f32_e32 v68, v42, v68
	v_mul_f32_e32 v69, v42, v69
	v_cvt_pk_bf16_f32 v29, v68, v69
	v_lshlrev_b32_e32 v66, 16, v30
	v_and_b32_e32 v67, 0xffff0000, v30
	v_mul_f32_e32 v66, v42, v66
	v_mul_f32_e32 v67, v42, v67
	v_cvt_pk_bf16_f32 v30, v66, v67
	v_lshlrev_b32_e32 v68, 16, v31
	v_and_b32_e32 v69, 0xffff0000, v31
	v_mul_f32_e32 v68, v42, v68
	v_mul_f32_e32 v69, v42, v69
	v_cvt_pk_bf16_f32 v31, v68, v69
	s_nop 1
	global_store_dwordx4 v[56:57], v[28:31], off
	s_waitcnt vmcnt(7)
	v_lshlrev_b32_e32 v66, 16, v32
	v_and_b32_e32 v67, 0xffff0000, v32
	v_mul_f32_e32 v66, v43, v66
	v_mul_f32_e32 v67, v43, v67
	v_cvt_pk_bf16_f32 v32, v66, v67
	v_lshlrev_b32_e32 v68, 16, v33
	v_and_b32_e32 v69, 0xffff0000, v33
	v_mul_f32_e32 v68, v43, v68
	v_mul_f32_e32 v69, v43, v69
	v_cvt_pk_bf16_f32 v33, v68, v69
	v_lshlrev_b32_e32 v66, 16, v34
	v_and_b32_e32 v67, 0xffff0000, v34
	v_mul_f32_e32 v66, v43, v66
	v_mul_f32_e32 v67, v43, v67
	v_cvt_pk_bf16_f32 v34, v66, v67
	v_lshlrev_b32_e32 v68, 16, v35
	v_and_b32_e32 v69, 0xffff0000, v35
	v_mul_f32_e32 v68, v43, v68
	v_mul_f32_e32 v69, v43, v69
	v_cvt_pk_bf16_f32 v35, v68, v69
	s_nop 1
	global_store_dwordx4 v[58:59], v[32:35], off
	v_lshl_add_u64 v[2:3], v[2:3], 0, s[2:3]
	s_add_u32 s0, s0, 0x2000
	s_addc_u32 s1, s1, 0
	s_cmpk_lg_u32 s0, 0x8000
	s_cbranch_scc1 .Lretfix_loop
	v_readlane_b32 s6, v249, 27
	v_readlane_b32 s7, v249, 28
	s_movk_i32 s2, 0x100
	s_mov_b64 s[0:1], 0
	s_and_b64 vcc, exec, s[6:7]
	s_cbranch_vccz .LBB0_1200
